# prep bias dot-product loop software-pipelined: 24 iterations of loads in flight with counted vmcnt instead of vmcnt(0) per iteration, same fmac order
# baseline (speedup 1.0000x reference)
; __device__ __forceinline__ float wave_sum(float v) {
; #pragma unroll
;     for (int o = 1; o < 64; o <<= 1) v += __shfl_xor(v, o);
;     return v;
; __device__ __forceinline__ void prep_phase(const Params& P, LAS unsigned char* lds) {
;     ...
;     for (int it = gw; it < DEPTH * 2 * 256; it += NGW) {
;         const int L = it >> 9, kv = (it >> 8) & 1, j = it & 255;
;         const float* pe = P.in[kv ? 6 : 3] + (size_t)L * 4096; const float* w1 = P.in[kv ? 7 : 4] + (size_t)L * 4096 * 256;
;         float s = 0.f; for (int i = lane; i < 4096; i += 64) s += pe[i] * w1[(size_t)i * 256 + j];
;         s = wave_sum(s); if (lane == 0) ((float*)(ws + WS_CB))[it] = s;
.LBB0_270:
	s_or_b64 exec, exec, s[14:15]
	s_movk_i32 s0, 0x400
	v_cmp_gt_i32_e32 vcc, s0, v2
	v_mbcnt_lo_u32_b32 v16, -1, 0
	s_and_saveexec_b64 s[6:7], vcc
	v_readlane_b32 s48, v255, 2
	v_readlane_b32 s60, v255, 4
	v_readlane_b32 s49, v255, 3
	v_readlane_b32 s61, v255, 5
	s_cbranch_execz .LBB0_277
	v_mbcnt_hi_u32_b32 v6, -1, v16
	v_lshrrev_b32_e32 v10, 6, v3
	v_and_b32_e32 v3, 64, v6
	v_add_u32_e32 v7, 64, v3
	v_xor_b32_e32 v3, 1, v6
	v_cmp_lt_i32_e32 vcc, v3, v7
	v_xor_b32_e32 v8, 2, v6
	s_add_u32 s14, s30, 0x39f00000
	v_cndmask_b32_e32 v3, v6, v3, vcc
	v_cmp_lt_i32_e32 vcc, v8, v7
	s_addc_u32 s15, s31, 0
	s_lshl_b32 s0, s89, 3
	v_cndmask_b32_e32 v8, v6, v8, vcc
	v_lshlrev_b32_e32 v17, 2, v8
	v_xor_b32_e32 v8, 4, v6
	v_cmp_lt_i32_e32 vcc, v8, v7
	v_lshlrev_b32_e32 v3, 2, v3
	v_or_b32_e32 v22, 0xffffffc0, v1
	v_cndmask_b32_e32 v8, v6, v8, vcc
	v_lshlrev_b32_e32 v18, 2, v8
	v_xor_b32_e32 v8, 8, v6
	v_cmp_lt_i32_e32 vcc, v8, v7
	v_add_u16_e32 v23, s0, v10
	s_mov_b64 s[16:17], 0
	v_cndmask_b32_e32 v8, v6, v8, vcc
	v_lshlrev_b32_e32 v19, 2, v8
	v_xor_b32_e32 v8, 16, v6
	v_cmp_lt_i32_e32 vcc, v8, v7
	v_mov_b32_e32 v24, s25
	v_mov_b32_e32 v25, s19
	v_cndmask_b32_e32 v8, v6, v8, vcc
	v_lshlrev_b32_e32 v20, 2, v8
	v_xor_b32_e32 v8, 32, v6
	v_cmp_lt_i32_e32 vcc, v8, v7
	v_mov_b32_e32 v7, 0
	v_mov_b32_e32 v9, v7
	v_cndmask_b32_e32 v6, v6, v8, vcc
	v_lshlrev_b32_e32 v21, 2, v6
	v_cmp_eq_u32_e32 vcc, 0, v1
	v_lshlrev_b32_e32 v6, 2, v1
	v_lshlrev_b32_e32 v8, 10, v1
	v_mov_b32_e32 v26, s24
	v_mov_b32_e32 v27, s18
	v_mov_b32_e32 v28, s27
	v_mov_b32_e32 v29, s21
	v_mov_b32_e32 v30, s26
	v_mov_b32_e32 v31, s20
	s_mov_b64 s[18:19], 0x1000
	s_mov_b64 s[20:21], 0x10000
	s_movk_i32 s0, 0xfbf
	s_movk_i32 s1, 0x3ff
	v_mov_b32_e32 v10, v2
	s_branch .LBB0_273

; __device__ __forceinline__ void prep_phase(const Params& P, LAS unsigned char* lds) {
;     ...
;         float s = 0.f; for (int i = lane; i < 4096; i += 64) s += pe[i] * w1[(size_t)i * 256 + j];
.Lbias_pipe_0:
	global_load_dword v53, v[12:13], off
	global_load_dword v54, v[14:15], off
	v_lshl_add_u64 v[14:15], v[14:15], 0, s[20:21]
	global_load_dword v55, v[12:13], off offset:256
	global_load_dword v56, v[14:15], off
	v_lshl_add_u64 v[14:15], v[14:15], 0, s[20:21]
	global_load_dword v57, v[12:13], off offset:512
	global_load_dword v58, v[14:15], off
	v_lshl_add_u64 v[14:15], v[14:15], 0, s[20:21]
	global_load_dword v59, v[12:13], off offset:768
	global_load_dword v60, v[14:15], off
	v_lshl_add_u64 v[14:15], v[14:15], 0, s[20:21]
	global_load_dword v61, v[12:13], off offset:1024
	global_load_dword v62, v[14:15], off
	v_lshl_add_u64 v[14:15], v[14:15], 0, s[20:21]
	global_load_dword v63, v[12:13], off offset:1280
	global_load_dword v64, v[14:15], off
	v_lshl_add_u64 v[14:15], v[14:15], 0, s[20:21]
	global_load_dword v65, v[12:13], off offset:1536
	global_load_dword v66, v[14:15], off
	v_lshl_add_u64 v[14:15], v[14:15], 0, s[20:21]
	global_load_dword v67, v[12:13], off offset:1792
	global_load_dword v68, v[14:15], off
	v_lshl_add_u64 v[14:15], v[14:15], 0, s[20:21]
	global_load_dword v69, v[12:13], off offset:2048
	global_load_dword v70, v[14:15], off
	v_lshl_add_u64 v[14:15], v[14:15], 0, s[20:21]
	global_load_dword v71, v[12:13], off offset:2304
	global_load_dword v72, v[14:15], off
	v_lshl_add_u64 v[14:15], v[14:15], 0, s[20:21]
	global_load_dword v73, v[12:13], off offset:2560
	global_load_dword v74, v[14:15], off
	v_lshl_add_u64 v[14:15], v[14:15], 0, s[20:21]
	global_load_dword v75, v[12:13], off offset:2816
	global_load_dword v76, v[14:15], off
	v_lshl_add_u64 v[14:15], v[14:15], 0, s[20:21]
	global_load_dword v77, v[12:13], off offset:3072
	global_load_dword v78, v[14:15], off
	v_lshl_add_u64 v[14:15], v[14:15], 0, s[20:21]
	global_load_dword v79, v[12:13], off offset:3328
	global_load_dword v80, v[14:15], off
	v_lshl_add_u64 v[14:15], v[14:15], 0, s[20:21]
	global_load_dword v81, v[12:13], off offset:3584
	global_load_dword v82, v[14:15], off
	v_lshl_add_u64 v[14:15], v[14:15], 0, s[20:21]
	global_load_dword v83, v[12:13], off offset:3840
	global_load_dword v84, v[14:15], off
	v_lshl_add_u64 v[14:15], v[14:15], 0, s[20:21]
	v_lshl_add_u64 v[12:13], v[12:13], 0, s[18:19]
	global_load_dword v85, v[12:13], off
	global_load_dword v86, v[14:15], off
	v_lshl_add_u64 v[14:15], v[14:15], 0, s[20:21]
	global_load_dword v87, v[12:13], off offset:256
	global_load_dword v88, v[14:15], off
	v_lshl_add_u64 v[14:15], v[14:15], 0, s[20:21]
	global_load_dword v89, v[12:13], off offset:512
	global_load_dword v90, v[14:15], off
	v_lshl_add_u64 v[14:15], v[14:15], 0, s[20:21]
	global_load_dword v91, v[12:13], off offset:768
	global_load_dword v92, v[14:15], off
	v_lshl_add_u64 v[14:15], v[14:15], 0, s[20:21]
	global_load_dword v93, v[12:13], off offset:1024
	global_load_dword v94, v[14:15], off
	v_lshl_add_u64 v[14:15], v[14:15], 0, s[20:21]
	global_load_dword v95, v[12:13], off offset:1280
	global_load_dword v96, v[14:15], off
	v_lshl_add_u64 v[14:15], v[14:15], 0, s[20:21]
	global_load_dword v97, v[12:13], off offset:1536
	global_load_dword v98, v[14:15], off
	v_lshl_add_u64 v[14:15], v[14:15], 0, s[20:21]
	global_load_dword v99, v[12:13], off offset:1792
	global_load_dword v100, v[14:15], off
	v_lshl_add_u64 v[14:15], v[14:15], 0, s[20:21]
	global_load_dword v101, v[12:13], off offset:2048
	global_load_dword v102, v[14:15], off
	v_lshl_add_u64 v[14:15], v[14:15], 0, s[20:21]
	s_waitcnt vmcnt(48)
	v_fmac_f32_e32 v11, v53, v54
	global_load_dword v103, v[12:13], off offset:2304
	global_load_dword v104, v[14:15], off
	v_lshl_add_u64 v[14:15], v[14:15], 0, s[20:21]
	s_waitcnt vmcnt(48)
	v_fmac_f32_e32 v11, v55, v56
	global_load_dword v105, v[12:13], off offset:2560
	global_load_dword v106, v[14:15], off
	v_lshl_add_u64 v[14:15], v[14:15], 0, s[20:21]
	s_waitcnt vmcnt(48)
	v_fmac_f32_e32 v11, v57, v58
	global_load_dword v107, v[12:13], off offset:2816
	global_load_dword v108, v[14:15], off
	v_lshl_add_u64 v[14:15], v[14:15], 0, s[20:21]
	s_waitcnt vmcnt(48)
	v_fmac_f32_e32 v11, v59, v60
	global_load_dword v109, v[12:13], off offset:3072
	global_load_dword v110, v[14:15], off
	v_lshl_add_u64 v[14:15], v[14:15], 0, s[20:21]
	s_waitcnt vmcnt(48)
	v_fmac_f32_e32 v11, v61, v62
	global_load_dword v111, v[12:13], off offset:3328
	global_load_dword v112, v[14:15], off
	v_lshl_add_u64 v[14:15], v[14:15], 0, s[20:21]
	s_waitcnt vmcnt(48)
	v_fmac_f32_e32 v11, v63, v64
	global_load_dword v113, v[12:13], off offset:3584
	global_load_dword v114, v[14:15], off
	v_lshl_add_u64 v[14:15], v[14:15], 0, s[20:21]
	s_waitcnt vmcnt(48)
	v_fmac_f32_e32 v11, v65, v66
	global_load_dword v115, v[12:13], off offset:3840
	global_load_dword v116, v[14:15], off
	v_lshl_add_u64 v[14:15], v[14:15], 0, s[20:21]
	v_lshl_add_u64 v[12:13], v[12:13], 0, s[18:19]
	s_waitcnt vmcnt(48)
	v_fmac_f32_e32 v11, v67, v68
	global_load_dword v53, v[12:13], off
	global_load_dword v54, v[14:15], off
	v_lshl_add_u64 v[14:15], v[14:15], 0, s[20:21]
	s_waitcnt vmcnt(48)
	v_fmac_f32_e32 v11, v69, v70
	global_load_dword v55, v[12:13], off offset:256
	global_load_dword v56, v[14:15], off
	v_lshl_add_u64 v[14:15], v[14:15], 0, s[20:21]
	s_waitcnt vmcnt(48)
	v_fmac_f32_e32 v11, v71, v72
	global_load_dword v57, v[12:13], off offset:512
	global_load_dword v58, v[14:15], off
	v_lshl_add_u64 v[14:15], v[14:15], 0, s[20:21]
	s_waitcnt vmcnt(48)
	v_fmac_f32_e32 v11, v73, v74
	global_load_dword v59, v[12:13], off offset:768
	global_load_dword v60, v[14:15], off
	v_lshl_add_u64 v[14:15], v[14:15], 0, s[20:21]
	s_waitcnt vmcnt(48)
; __device__ __forceinline__ void prep_phase(const Params& P, LAS unsigned char* lds) {
;     ...
;         float s = 0.f; for (int i = lane; i < 4096; i += 64) s += pe[i] * w1[(size_t)i * 256 + j];
	v_fmac_f32_e32 v11, v75, v76
	global_load_dword v61, v[12:13], off offset:1024
	global_load_dword v62, v[14:15], off
	v_lshl_add_u64 v[14:15], v[14:15], 0, s[20:21]
	s_waitcnt vmcnt(48)
	v_fmac_f32_e32 v11, v77, v78
	global_load_dword v63, v[12:13], off offset:1280
	global_load_dword v64, v[14:15], off
	v_lshl_add_u64 v[14:15], v[14:15], 0, s[20:21]
	s_waitcnt vmcnt(48)
	v_fmac_f32_e32 v11, v79, v80
	global_load_dword v65, v[12:13], off offset:1536
	global_load_dword v66, v[14:15], off
	v_lshl_add_u64 v[14:15], v[14:15], 0, s[20:21]
	s_waitcnt vmcnt(48)
	v_fmac_f32_e32 v11, v81, v82
	global_load_dword v67, v[12:13], off offset:1792
	global_load_dword v68, v[14:15], off
	v_lshl_add_u64 v[14:15], v[14:15], 0, s[20:21]
	s_waitcnt vmcnt(48)
	v_fmac_f32_e32 v11, v83, v84
	global_load_dword v69, v[12:13], off offset:2048
	global_load_dword v70, v[14:15], off
	v_lshl_add_u64 v[14:15], v[14:15], 0, s[20:21]
	s_waitcnt vmcnt(48)
	v_fmac_f32_e32 v11, v85, v86
	global_load_dword v71, v[12:13], off offset:2304
	global_load_dword v72, v[14:15], off
	v_lshl_add_u64 v[14:15], v[14:15], 0, s[20:21]
	s_waitcnt vmcnt(48)
	v_fmac_f32_e32 v11, v87, v88
	global_load_dword v73, v[12:13], off offset:2560
	global_load_dword v74, v[14:15], off
	v_lshl_add_u64 v[14:15], v[14:15], 0, s[20:21]
	s_waitcnt vmcnt(48)
	v_fmac_f32_e32 v11, v89, v90
	global_load_dword v75, v[12:13], off offset:2816
	global_load_dword v76, v[14:15], off
	v_lshl_add_u64 v[14:15], v[14:15], 0, s[20:21]
	s_waitcnt vmcnt(48)
	v_fmac_f32_e32 v11, v91, v92
	global_load_dword v77, v[12:13], off offset:3072
	global_load_dword v78, v[14:15], off
	v_lshl_add_u64 v[14:15], v[14:15], 0, s[20:21]
	s_waitcnt vmcnt(48)
	v_fmac_f32_e32 v11, v93, v94
	global_load_dword v79, v[12:13], off offset:3328
	global_load_dword v80, v[14:15], off
	v_lshl_add_u64 v[14:15], v[14:15], 0, s[20:21]
	s_waitcnt vmcnt(48)
	v_fmac_f32_e32 v11, v95, v96
	global_load_dword v81, v[12:13], off offset:3584
	global_load_dword v82, v[14:15], off
	v_lshl_add_u64 v[14:15], v[14:15], 0, s[20:21]
	s_waitcnt vmcnt(48)
	v_fmac_f32_e32 v11, v97, v98
	global_load_dword v83, v[12:13], off offset:3840
	global_load_dword v84, v[14:15], off
	v_lshl_add_u64 v[14:15], v[14:15], 0, s[20:21]
	v_lshl_add_u64 v[12:13], v[12:13], 0, s[18:19]
	s_waitcnt vmcnt(48)
	v_fmac_f32_e32 v11, v99, v100
	global_load_dword v85, v[12:13], off
	global_load_dword v86, v[14:15], off
	v_lshl_add_u64 v[14:15], v[14:15], 0, s[20:21]
	s_waitcnt vmcnt(48)
	v_fmac_f32_e32 v11, v101, v102
	global_load_dword v87, v[12:13], off offset:256
	global_load_dword v88, v[14:15], off
	v_lshl_add_u64 v[14:15], v[14:15], 0, s[20:21]
	s_waitcnt vmcnt(48)
	v_fmac_f32_e32 v11, v103, v104
	global_load_dword v89, v[12:13], off offset:512
	global_load_dword v90, v[14:15], off
	v_lshl_add_u64 v[14:15], v[14:15], 0, s[20:21]
	s_waitcnt vmcnt(48)
	v_fmac_f32_e32 v11, v105, v106
	global_load_dword v91, v[12:13], off offset:768
	global_load_dword v92, v[14:15], off
	v_lshl_add_u64 v[14:15], v[14:15], 0, s[20:21]
	s_waitcnt vmcnt(48)
	v_fmac_f32_e32 v11, v107, v108
	global_load_dword v93, v[12:13], off offset:1024
	global_load_dword v94, v[14:15], off
	v_lshl_add_u64 v[14:15], v[14:15], 0, s[20:21]
	s_waitcnt vmcnt(48)
	v_fmac_f32_e32 v11, v109, v110
	global_load_dword v95, v[12:13], off offset:1280
	global_load_dword v96, v[14:15], off
	v_lshl_add_u64 v[14:15], v[14:15], 0, s[20:21]
	s_waitcnt vmcnt(48)
	v_fmac_f32_e32 v11, v111, v112
	global_load_dword v97, v[12:13], off offset:1536
	global_load_dword v98, v[14:15], off
	v_lshl_add_u64 v[14:15], v[14:15], 0, s[20:21]
	s_waitcnt vmcnt(48)
; __device__ __forceinline__ float wave_sum(float v) {
; #pragma unroll
;     for (int o = 1; o < 64; o <<= 1) v += __shfl_xor(v, o);
;     return v;
; __device__ __forceinline__ void prep_phase(const Params& P, LAS unsigned char* lds) {
;     ...
;         float s = 0.f; for (int i = lane; i < 4096; i += 64) s += pe[i] * w1[(size_t)i * 256 + j];
;         s = wave_sum(s); if (lane == 0) ((float*)(ws + WS_CB))[it] = s;
	v_fmac_f32_e32 v11, v113, v114
	global_load_dword v99, v[12:13], off offset:1792
	global_load_dword v100, v[14:15], off
	v_lshl_add_u64 v[14:15], v[14:15], 0, s[20:21]
	s_waitcnt vmcnt(48)
	v_fmac_f32_e32 v11, v115, v116
	global_load_dword v101, v[12:13], off offset:2048
	global_load_dword v102, v[14:15], off
	v_lshl_add_u64 v[14:15], v[14:15], 0, s[20:21]
	s_waitcnt vmcnt(48)
	v_fmac_f32_e32 v11, v53, v54
	global_load_dword v103, v[12:13], off offset:2304
	global_load_dword v104, v[14:15], off
	v_lshl_add_u64 v[14:15], v[14:15], 0, s[20:21]
	s_waitcnt vmcnt(48)
	v_fmac_f32_e32 v11, v55, v56
	global_load_dword v105, v[12:13], off offset:2560
	global_load_dword v106, v[14:15], off
	v_lshl_add_u64 v[14:15], v[14:15], 0, s[20:21]
	s_waitcnt vmcnt(48)
	v_fmac_f32_e32 v11, v57, v58
	global_load_dword v107, v[12:13], off offset:2816
	global_load_dword v108, v[14:15], off
	v_lshl_add_u64 v[14:15], v[14:15], 0, s[20:21]
	s_waitcnt vmcnt(48)
	v_fmac_f32_e32 v11, v59, v60
	global_load_dword v109, v[12:13], off offset:3072
	global_load_dword v110, v[14:15], off
	v_lshl_add_u64 v[14:15], v[14:15], 0, s[20:21]
	s_waitcnt vmcnt(48)
	v_fmac_f32_e32 v11, v61, v62
	global_load_dword v111, v[12:13], off offset:3328
	global_load_dword v112, v[14:15], off
	v_lshl_add_u64 v[14:15], v[14:15], 0, s[20:21]
	s_waitcnt vmcnt(48)
	v_fmac_f32_e32 v11, v63, v64
	global_load_dword v113, v[12:13], off offset:3584
	global_load_dword v114, v[14:15], off
	v_lshl_add_u64 v[14:15], v[14:15], 0, s[20:21]
	s_waitcnt vmcnt(48)
	v_fmac_f32_e32 v11, v65, v66
	global_load_dword v115, v[12:13], off offset:3840
	global_load_dword v116, v[14:15], off
	v_lshl_add_u64 v[14:15], v[14:15], 0, s[20:21]
	v_lshl_add_u64 v[12:13], v[12:13], 0, s[18:19]
	s_waitcnt vmcnt(48)
	v_fmac_f32_e32 v11, v67, v68
	s_waitcnt vmcnt(46)
	v_fmac_f32_e32 v11, v69, v70
	s_waitcnt vmcnt(44)
	v_fmac_f32_e32 v11, v71, v72
	s_waitcnt vmcnt(42)
	v_fmac_f32_e32 v11, v73, v74
	s_waitcnt vmcnt(40)
	v_fmac_f32_e32 v11, v75, v76
	s_waitcnt vmcnt(38)
	v_fmac_f32_e32 v11, v77, v78
	s_waitcnt vmcnt(36)
	v_fmac_f32_e32 v11, v79, v80
	s_waitcnt vmcnt(34)
	v_fmac_f32_e32 v11, v81, v82
	s_waitcnt vmcnt(32)
	v_fmac_f32_e32 v11, v83, v84
	s_waitcnt vmcnt(30)
	v_fmac_f32_e32 v11, v85, v86
	s_waitcnt vmcnt(28)
	v_fmac_f32_e32 v11, v87, v88
	s_waitcnt vmcnt(26)
	v_fmac_f32_e32 v11, v89, v90
	s_waitcnt vmcnt(24)
	v_fmac_f32_e32 v11, v91, v92
	s_waitcnt vmcnt(22)
	v_fmac_f32_e32 v11, v93, v94
	s_waitcnt vmcnt(20)
	v_fmac_f32_e32 v11, v95, v96
	s_waitcnt vmcnt(18)
	v_fmac_f32_e32 v11, v97, v98
	s_waitcnt vmcnt(16)
	v_fmac_f32_e32 v11, v99, v100
	s_waitcnt vmcnt(14)
	v_fmac_f32_e32 v11, v101, v102
	s_waitcnt vmcnt(12)
	v_fmac_f32_e32 v11, v103, v104
	s_waitcnt vmcnt(10)
	v_fmac_f32_e32 v11, v105, v106
	s_waitcnt vmcnt(8)
	v_fmac_f32_e32 v11, v107, v108
	s_waitcnt vmcnt(6)
	v_fmac_f32_e32 v11, v109, v110
	s_waitcnt vmcnt(4)
	v_fmac_f32_e32 v11, v111, v112
	s_waitcnt vmcnt(2)
	v_fmac_f32_e32 v11, v113, v114
	s_waitcnt vmcnt(0)
	v_fmac_f32_e32 v11, v115, v116
	ds_bpermute_b32 v12, v3, v11
	s_waitcnt lgkmcnt(0)
	v_add_f32_e32 v11, v11, v12
	ds_bpermute_b32 v12, v17, v11
	s_waitcnt lgkmcnt(0)
	v_add_f32_e32 v11, v11, v12
	ds_bpermute_b32 v12, v18, v11
	s_waitcnt lgkmcnt(0)
	v_add_f32_e32 v11, v11, v12
	ds_bpermute_b32 v12, v19, v11
	s_waitcnt lgkmcnt(0)
	v_add_f32_e32 v11, v11, v12
	ds_bpermute_b32 v12, v20, v11
	s_waitcnt lgkmcnt(0)
	v_add_f32_e32 v11, v11, v12
	ds_bpermute_b32 v12, v21, v11
	s_and_saveexec_b64 s[4:5], vcc
	s_cbranch_execz .LBB0_272
	s_waitcnt lgkmcnt(0)
	v_add_f32_e32 v14, v11, v12
	v_ashrrev_i32_e32 v11, 31, v10
	v_lshl_add_u64 v[12:13], v[10:11], 2, s[14:15]
	global_store_dword v[12:13], v14, off
	s_branch .LBB0_272
